# attncsel + GEMM unit head: first K-tile LDS fragment reads of units>=2 issued before the unit-head scalar work (overlaps LDS latency with SALU)
# baseline (speedup 1.0000x reference)
;     __device__ __forceinline__ void prefetch(Pre& p, const Unit& u, int wr, int fr, int fq) const { prefetch_ss(p, ss, u, wr, fr, fq); }
;     __device__ __forceinline__ void prefetch(Pre& p, const Unit& u, int wr, int fr, int fq) const { prefetch_ss(p, ss, u, wr, fr, fq); }
;     __device__ __forceinline__ void prefetch(Pre& p, const Unit& u, int wr, int fr, int fq) const { prefetch_ss(p, ss, u, wr, fr, fq); }
; #define PG8_STAGE(bufoff, gbase, voff) do { _Pragma("unroll") for (int _i = 0; _i < 2; ++_i) \
;         __builtin_amdgcn_global_load_lds((const unsigned*)((const char*)(gbase) + (voff)[_i]), (PG8_LAS unsigned*)(lds + (bufoff) + ldsw + _i * 8192), 16, 0, 0); } while (0)
; #define PG8_SCHED __builtin_amdgcn_sched_barrier(0)
;     __host__ __device__ bool next(int i, Unit& u) const {
;         const long L = (long)i * G + c; if (L >= nwg) return false;
;         int wgid = (int)L; { const int q = nwg / NXCD, r = nwg % NXCD, xcd = wgid % NXCD, off = wgid / NXCD; wgid = (xcd < r ? xcd * (q + 1) : r * (q + 1) + (xcd - r) * q) + off; }
;         const int nig = WGM * nN, gid = wgid / nig, fm = gid * WGM, gsz = (nM - fm) < WGM ? (nM - fm) : WGM;
;         u.pm = fm + ((wgid % nig) % gsz); u.pn = (wgid % nig) / gsz; return true;
;     }
; template <class Epi, class Sched, bool ALIGN_EPI = false, bool SP2 = false>
; __device__ __forceinline__ void gemm_phase(PG8_LAS unsigned char* lds, const Gemm g, const Sched& S, const Epi& E) {
;     ...
;         const bool has_next = S.next(ui + 1, nxt);
;         typename Epi::Pre pre; E.prefetch(pre, cur, wr, fr, fq);
;         const char* nA = has_next ? (const char*)g.A + (size_t)nxt.pm * tstep : cA; const char* nB = has_next ? (const char*)g.Bt + (size_t)nxt.pn * tstep : cB;
;         for (int t = 0; t < nt; t += 2) {
;             const bool last = (t == nt - 2);
;             const char* a1 = cA + (size_t)(t + 1) * kstep;
;             const char* a2 = last ? nA : cA + (size_t)(t + 2) * kstep; const char* b2 = last ? nB : cB + (size_t)(t + 2) * kstep;
;             const char* a3 = a2 + kstep; const char* b3 = b2 + kstep;
;             if (last && has_next) S.a_ready(nxt);
;             if constexpr (SP2) {
;             PG8_LDB(B0, 0, 0); PG8_LDB(B1, 0, 1); PG8_SCHED; PG8_LDA(At, 0, 0); PG8_STAGE(PG8_SA(1, 1), a1 + hstep, voffA);
.LBB0_47:
	s_add_i32 s75, s75, 1
	v_readlane_b32 s5, v252, 14
	s_mul_i32 s5, s75, s5
	s_mul_hi_u32 s10, s75, s9
	s_add_i32 s10, s10, s5
	s_mul_i32 s5, s75, s9
	s_add_u32 s26, s5, s76
	v_readlane_b32 s5, v254, 23
	s_addc_u32 s27, s10, s5
	s_waitcnt lgkmcnt(0)
	s_cmp_eq_u32 s75, 1
	s_cbranch_scc1 .Lnohoist_g1o
	v_add_u32_e32 v154, 0x10000, v157
	ds_read_b128 v[162:165], v154
	ds_read_b128 v[166:169], v154 offset:1024
	ds_read_b128 v[170:173], v154 offset:2048
	ds_read_b128 v[174:177], v154 offset:3072
	v_add_u32_e32 v154, 0x14000, v157
	ds_read_b128 v[178:181], v154
	ds_read_b128 v[182:185], v154 offset:1024
	ds_read_b128 v[186:189], v154 offset:2048
	ds_read_b128 v[190:193], v154 offset:3072
	ds_read_b128 v[200:203], v161
	ds_read_b128 v[204:207], v161 offset:1024
	ds_read_b128 v[208:211], v161 offset:2048
	ds_read_b128 v[212:215], v161 offset:3072
	ds_read_b128 v[216:219], v161 offset:4096
	ds_read_b128 v[220:223], v161 offset:5120
	ds_read_b128 v[224:227], v161 offset:6144
	ds_read_b128 v[228:231], v161 offset:7168
.Lnohoist_g1o:
	v_mov_b64_e32 v[0:1], 0x800
	v_cmp_lt_i64_e64 s[42:43], s[26:27], v[0:1]
	v_mov_b64_e32 v[0:1], 0x7ff
	v_cmp_gt_i64_e32 vcc, s[26:27], v[0:1]
	s_cbranch_vccnz .LBB0_53
	s_ashr_i32 s5, s26, 31
	s_lshr_b32 s5, s5, 29
	s_add_i32 s10, s26, s5
	s_and_b32 s5, s10, -8
	s_sub_i32 s12, s26, s5
	s_cmp_gt_i32 s12, -1
	s_mov_b64 s[26:27], -1
	s_cbranch_scc0 .LBB0_50
	s_lshl_b32 s14, s12, 8
	s_mov_b64 s[26:27], 0

; #define PG8_STAGE(bufoff, gbase, voff) do { _Pragma("unroll") for (int _i = 0; _i < 2; ++_i) \
;         __builtin_amdgcn_global_load_lds((const unsigned*)((const char*)(gbase) + (voff)[_i]), (PG8_LAS unsigned*)(lds + (bufoff) + ldsw + _i * 8192), 16, 0, 0); } while (0)
; #define PG8_LDA(dst, b, h) do { _Pragma("unroll") for (int m = 0; m < 4; ++m) _Pragma("unroll") for (int k = 0; k < 2; ++k) dst[m][k] = *(const PG8_LAS bf16x8*)(lds + PG8_SA(b, h) + aoff + m * 2048 + k * 1024); } while (0)
; #define PG8_LDB(dst, b, h) do { _Pragma("unroll") for (int n = 0; n < 2; ++n) _Pragma("unroll") for (int k = 0; k < 2; ++k) dst[n][k] = *(const PG8_LAS bf16x8*)(lds + PG8_SB(b, h) + boff + n * 2048 + k * 1024); } while (0)
; #define PG8_MMA(ai, bj, At, Bt) do { __builtin_amdgcn_s_setprio(1); _Pragma("unroll") for (int m = 0; m < 4; ++m) _Pragma("unroll") for (int n = 0; n < 2; ++n) _Pragma("unroll") for (int k = 0; k < 2; ++k) \
;         acc[ai][bj][m][n] = __builtin_amdgcn_mfma_f32_16x16x32_bf16(Bt[n][k], At[m][k], acc[ai][bj][m][n], 0, 0, 0); __builtin_amdgcn_s_setprio(0); } while (0)
; #define PG8_WAIT_V(n) asm volatile("s_waitcnt vmcnt(" #n ")" ::: "memory")
; #define PG8_WAIT_L(n) asm volatile("s_waitcnt lgkmcnt(" #n ")" ::: "memory")
; #define PG8_BAR __builtin_amdgcn_s_barrier()
; #define PG8_SCHED __builtin_amdgcn_sched_barrier(0)
; template <class Epi, class Sched, bool ALIGN_EPI = false, bool SP2 = false>
; __device__ __forceinline__ void gemm_phase(PG8_LAS unsigned char* lds, const Gemm g, const Sched& S, const Epi& E) {
;     ...
;             PG8_LDB(B0, 0, 0); PG8_LDB(B1, 0, 1); PG8_SCHED; PG8_LDA(At, 0, 0); PG8_STAGE(PG8_SA(1, 1), a1 + hstep, voffA);
;             PG8_WAIT_V(8); PG8_WAIT_L(0); PG8_BAR; PG8_MMA(0, 0, At, B0); PG8_MMA(0, 1, At, B1); PG8_BAR; PG8_SCHED;
;             PG8_LDA(At, 0, 1); PG8_STAGE(PG8_SB(0, 0), b2, voffB); PG8_STAGE(PG8_SB(0, 1), b2 + hstep, voffB); PG8_STAGE(PG8_SA(0, 0), a2, voffA);
;             PG8_WAIT_V(8); PG8_WAIT_L(0); PG8_BAR; PG8_MMA(1, 0, At, B0); PG8_MMA(1, 1, At, B1); PG8_BAR; PG8_SCHED;
.Lpeel_g1o:
	s_add_u32 s5, s44, 0xfffc0080
	s_addc_u32 s8, s45, -1
	s_add_i32 s10, 0, 0x10000
	s_cmp_eq_u32 s76, 12
	s_cselect_b32 s67, s26, s8
	s_cselect_b32 s66, s27, s5
	s_cselect_b32 s65, s36, s59
	s_cselect_b32 s64, s39, s57
	s_add_i32 s5, 0, 0x14000
	v_lshl_add_u64 v[194:195], s[44:45], 0, v[140:141]
	s_add_i32 m0, s69, 0xc000
	global_load_lds_dwordx4 v[194:195], off
	v_lshl_add_u64 v[194:195], s[44:45], 0, v[138:139]
	s_add_i32 m0, s69, 0xe000
	s_nop 0
	global_load_lds_dwordx4 v[194:195], off
	s_waitcnt vmcnt(26)
	s_waitcnt lgkmcnt(0)
	s_barrier
	s_setprio 1
	s_waitcnt lgkmcnt(0)
	v_mfma_f32_16x16x32_bf16 v[124:127], v[162:165], v[200:203], 0
	v_mfma_f32_16x16x32_bf16 v[120:123], v[170:173], v[200:203], 0
	v_mfma_f32_16x16x32_bf16 v[108:111], v[162:165], v[208:211], 0
	v_mfma_f32_16x16x32_bf16 v[104:107], v[170:173], v[208:211], 0
	v_mfma_f32_16x16x32_bf16 v[92:95], v[162:165], v[216:219], 0
	v_mfma_f32_16x16x32_bf16 v[88:91], v[170:173], v[216:219], 0
	v_mfma_f32_16x16x32_bf16 v[76:79], v[162:165], v[224:227], 0
	v_mfma_f32_16x16x32_bf16 v[72:75], v[170:173], v[224:227], 0
	v_mfma_f32_16x16x32_bf16 v[124:127], v[166:169], v[204:207], v[124:127]
	v_mfma_f32_16x16x32_bf16 v[120:123], v[174:177], v[204:207], v[120:123]
	v_mfma_f32_16x16x32_bf16 v[108:111], v[166:169], v[212:215], v[108:111]
	v_mfma_f32_16x16x32_bf16 v[104:107], v[174:177], v[212:215], v[104:107]
	v_mfma_f32_16x16x32_bf16 v[92:95], v[166:169], v[220:223], v[92:95]
	v_mfma_f32_16x16x32_bf16 v[88:91], v[174:177], v[220:223], v[88:91]
	v_mfma_f32_16x16x32_bf16 v[76:79], v[166:169], v[228:231], v[76:79]
	v_mfma_f32_16x16x32_bf16 v[72:75], v[174:177], v[228:231], v[72:75]
	s_setprio 0
	s_setprio 1
	v_mfma_f32_16x16x32_bf16 v[116:119], v[178:181], v[200:203], 0
	v_mfma_f32_16x16x32_bf16 v[112:115], v[186:189], v[200:203], 0
	v_mfma_f32_16x16x32_bf16 v[100:103], v[178:181], v[208:211], 0
	v_mfma_f32_16x16x32_bf16 v[96:99], v[186:189], v[208:211], 0
	v_mfma_f32_16x16x32_bf16 v[84:87], v[178:181], v[216:219], 0
	v_mfma_f32_16x16x32_bf16 v[80:83], v[186:189], v[216:219], 0
	v_mfma_f32_16x16x32_bf16 v[68:71], v[178:181], v[224:227], 0
	v_mfma_f32_16x16x32_bf16 v[64:67], v[186:189], v[224:227], 0
	v_mfma_f32_16x16x32_bf16 v[116:119], v[182:185], v[204:207], v[116:119]
	v_mfma_f32_16x16x32_bf16 v[112:115], v[190:193], v[204:207], v[112:115]
	v_mfma_f32_16x16x32_bf16 v[100:103], v[182:185], v[212:215], v[100:103]
	v_mfma_f32_16x16x32_bf16 v[96:99], v[190:193], v[212:215], v[96:99]
	v_mfma_f32_16x16x32_bf16 v[84:87], v[182:185], v[220:223], v[84:87]
	v_mfma_f32_16x16x32_bf16 v[80:83], v[190:193], v[220:223], v[80:83]
	v_mfma_f32_16x16x32_bf16 v[68:71], v[182:185], v[228:231], v[68:71]
	v_mfma_f32_16x16x32_bf16 v[64:67], v[190:193], v[228:231], v[64:67]
	s_setprio 0
	s_barrier
	s_add_i32 s8, s10, s68
	v_lshl_add_u64 v[194:195], s[64:65], 0, v[132:133]
	s_mov_b32 m0, s8
	ds_read_b128 v[200:203], v161 offset:16384
	ds_read_b128 v[204:207], v161 offset:17408
	ds_read_b128 v[208:211], v161 offset:18432
	ds_read_b128 v[212:215], v161 offset:19456
	ds_read_b128 v[216:219], v161 offset:20480
	ds_read_b128 v[220:223], v161 offset:21504
	ds_read_b128 v[224:227], v161 offset:22528
	ds_read_b128 v[228:231], v161 offset:23552
	global_load_lds_dwordx4 v[194:195], off
	s_add_i32 m0, s8, 0x2000
	s_add_u32 s20, s64, 0x40000
	v_lshl_add_u64 v[240:241], s[64:65], 0, v[128:129]
	s_addc_u32 s21, s65, 0
	s_add_i32 s5, s5, s68
	global_load_lds_dwordx4 v[240:241], off
	v_lshl_add_u64 v[242:243], s[20:21], 0, v[132:133]
	s_mov_b32 m0, s5
	v_lshl_add_u64 v[244:245], s[66:67], 0, v[130:131]
	global_load_lds_dwordx4 v[242:243], off
	v_lshl_add_u64 v[242:243], s[20:21], 0, v[128:129]
	s_add_i32 m0, s5, 0x2000
	s_nop 0
	global_load_lds_dwordx4 v[242:243], off
	v_lshl_add_u64 v[242:243], s[66:67], 0, v[134:135]
	s_mov_b32 m0, s69
	s_nop 0
	global_load_lds_dwordx4 v[242:243], off
	s_mov_b32 m0, s70
	s_nop 0
	global_load_lds_dwordx4 v[244:245], off
	s_waitcnt vmcnt(26)
	s_waitcnt lgkmcnt(0)
	s_barrier
	s_setprio 1
	s_waitcnt lgkmcnt(0)
	v_mfma_f32_16x16x32_bf16 v[60:63], v[162:165], v[200:203], 0
	v_mfma_f32_16x16x32_bf16 v[56:59], v[170:173], v[200:203], 0
	v_mfma_f32_16x16x32_bf16 v[44:47], v[162:165], v[208:211], 0
	v_mfma_f32_16x16x32_bf16 v[40:43], v[170:173], v[208:211], 0
	v_mfma_f32_16x16x32_bf16 v[28:31], v[162:165], v[216:219], 0
	v_mfma_f32_16x16x32_bf16 v[24:27], v[170:173], v[216:219], 0
	v_mfma_f32_16x16x32_bf16 v[12:15], v[162:165], v[224:227], 0
	v_mfma_f32_16x16x32_bf16 v[8:11], v[170:173], v[224:227], 0
	v_mfma_f32_16x16x32_bf16 v[60:63], v[166:169], v[204:207], v[60:63]
	v_mfma_f32_16x16x32_bf16 v[56:59], v[174:177], v[204:207], v[56:59]
	v_mfma_f32_16x16x32_bf16 v[44:47], v[166:169], v[212:215], v[44:47]
	v_mfma_f32_16x16x32_bf16 v[40:43], v[174:177], v[212:215], v[40:43]
	v_mfma_f32_16x16x32_bf16 v[28:31], v[166:169], v[220:223], v[28:31]
	v_mfma_f32_16x16x32_bf16 v[24:27], v[174:177], v[220:223], v[24:27]
	v_mfma_f32_16x16x32_bf16 v[12:15], v[166:169], v[228:231], v[12:15]
	v_mfma_f32_16x16x32_bf16 v[8:11], v[174:177], v[228:231], v[8:11]
	s_setprio 0
	s_setprio 1
	v_mfma_f32_16x16x32_bf16 v[52:55], v[178:181], v[200:203], 0
	v_mfma_f32_16x16x32_bf16 v[48:51], v[186:189], v[200:203], 0
	v_mfma_f32_16x16x32_bf16 v[36:39], v[178:181], v[208:211], 0
	v_mfma_f32_16x16x32_bf16 v[32:35], v[186:189], v[208:211], 0
	v_mfma_f32_16x16x32_bf16 v[20:23], v[178:181], v[216:219], 0
	v_mfma_f32_16x16x32_bf16 v[16:19], v[186:189], v[216:219], 0
	v_mfma_f32_16x16x32_bf16 v[4:7], v[178:181], v[224:227], 0
	v_mfma_f32_16x16x32_bf16 v[0:3], v[186:189], v[224:227], 0
	v_mfma_f32_16x16x32_bf16 v[52:55], v[182:185], v[204:207], v[52:55]
	v_mfma_f32_16x16x32_bf16 v[48:51], v[190:193], v[204:207], v[48:51]
	v_mfma_f32_16x16x32_bf16 v[36:39], v[182:185], v[212:215], v[36:39]
	v_mfma_f32_16x16x32_bf16 v[32:35], v[190:193], v[212:215], v[32:35]
	v_mfma_f32_16x16x32_bf16 v[20:23], v[182:185], v[220:223], v[20:23]
	v_mfma_f32_16x16x32_bf16 v[16:19], v[190:193], v[220:223], v[16:19]
	v_mfma_f32_16x16x32_bf16 v[4:7], v[182:185], v[228:231], v[4:7]
	v_mfma_f32_16x16x32_bf16 v[0:3], v[190:193], v[228:231], v[0:3]
	s_setprio 0
	s_barrier
	s_branch .Lmid_g1o

;     __device__ __forceinline__ void prefetch(Pre& p, const Unit& u, int wr, int fr, int fq) const { prefetch_ss(p, ss, u, wr, fr, fq); }
;     __device__ __forceinline__ void prefetch(Pre& p, const Unit& u, int wr, int fr, int fq) const { prefetch_ss(p, ss, u, wr, fr, fq); }
;     __device__ __forceinline__ void prefetch(Pre& p, const Unit& u, int wr, int fr, int fq) const { prefetch_ss(p, ss, u, wr, fr, fq); }
; #define PG8_STAGE(bufoff, gbase, voff) do { _Pragma("unroll") for (int _i = 0; _i < 2; ++_i) \
;         __builtin_amdgcn_global_load_lds((const unsigned*)((const char*)(gbase) + (voff)[_i]), (PG8_LAS unsigned*)(lds + (bufoff) + ldsw + _i * 8192), 16, 0, 0); } while (0)
; #define PG8_SCHED __builtin_amdgcn_sched_barrier(0)
;     __host__ __device__ bool next(int i, Unit& u) const {
;         const long L = (long)i * G + c; if (L >= nwg) return false;
;         int wgid = (int)L; { const int q = nwg / NXCD, r = nwg % NXCD, xcd = wgid % NXCD, off = wgid / NXCD; wgid = (xcd < r ? xcd * (q + 1) : r * (q + 1) + (xcd - r) * q) + off; }
;         const int nig = WGM * nN, gid = wgid / nig, fm = gid * WGM, gsz = (nM - fm) < WGM ? (nM - fm) : WGM;
;         u.pm = fm + ((wgid % nig) % gsz); u.pn = (wgid % nig) / gsz; return true;
;     }
; template <class Epi, class Sched, bool ALIGN_EPI = false, bool SP2 = false>
; __device__ __forceinline__ void gemm_phase(PG8_LAS unsigned char* lds, const Gemm g, const Sched& S, const Epi& E) {
;     ...
;         const bool has_next = S.next(ui + 1, nxt);
;         typename Epi::Pre pre; E.prefetch(pre, cur, wr, fr, fq);
;         const char* nA = has_next ? (const char*)g.A + (size_t)nxt.pm * tstep : cA; const char* nB = has_next ? (const char*)g.Bt + (size_t)nxt.pn * tstep : cB;
;         for (int t = 0; t < nt; t += 2) {
;             const bool last = (t == nt - 2);
;             const char* a1 = cA + (size_t)(t + 1) * kstep;
;             const char* a2 = last ? nA : cA + (size_t)(t + 2) * kstep; const char* b2 = last ? nB : cB + (size_t)(t + 2) * kstep;
;             const char* a3 = a2 + kstep; const char* b3 = b2 + kstep;
;             if (last && has_next) S.a_ready(nxt);
;             if constexpr (SP2) {
;             PG8_LDB(B0, 0, 0); PG8_LDB(B1, 0, 1); PG8_SCHED; PG8_LDA(At, 0, 0); PG8_STAGE(PG8_SA(1, 1), a1 + hstep, voffA);
.LBB0_101:
	s_add_i32 s73, s73, 1
	v_readlane_b32 s0, v252, 14
	s_mul_i32 s0, s73, s0
	s_mul_hi_u32 s1, s73, s9
	s_add_i32 s1, s1, s0
	s_mul_i32 s0, s73, s9
	s_add_u32 s26, s0, s76
	v_readlane_b32 s0, v254, 23
	s_addc_u32 s27, s1, s0
	s_waitcnt lgkmcnt(0)
	s_cmp_eq_u32 s73, 1
	s_cbranch_scc1 .Lnohoist_g4
	v_add_u32_e32 v124, 0x10000, v240
	v_add_u32_e32 v156, 0x14000, v240
	ds_read_b128 v[112:115], v124
	ds_read_b128 v[116:119], v124 offset:1024
	ds_read_b128 v[120:123], v124 offset:2048
	ds_read_b128 v[124:127], v124 offset:3072
	ds_read_b128 v[132:135], v156
	ds_read_b128 v[140:143], v156 offset:1024
	ds_read_b128 v[152:155], v156 offset:2048
	ds_read_b128 v[156:159], v156 offset:3072
	ds_read_b128 v[164:167], v242
	ds_read_b128 v[172:175], v242 offset:1024
	ds_read_b128 v[176:179], v242 offset:2048
	ds_read_b128 v[180:183], v242 offset:3072
	ds_read_b128 v[184:187], v242 offset:4096
	ds_read_b128 v[188:191], v242 offset:5120
	ds_read_b128 v[192:195], v242 offset:6144
	ds_read_b128 v[210:213], v242 offset:7168
.Lnohoist_g4:
	v_mov_b64_e32 v[0:1], 0x3ff
	v_cmp_gt_i64_e32 vcc, s[26:27], v[0:1]
	v_cmp_lt_i64_e64 s[0:1], s[26:27], v[198:199]
	s_cbranch_vccnz .LBB0_107
	s_ashr_i32 s5, s26, 31
	s_lshr_b32 s5, s5, 29
	s_add_i32 s8, s26, s5
	s_and_b32 s5, s8, -8
	s_sub_i32 s10, s26, s5
	s_cmp_gt_i32 s10, -1
	s_mov_b64 s[26:27], -1
	s_cbranch_scc0 .LBB0_104
	s_lshl_b32 s12, s10, 7
	s_mov_b64 s[26:27], 0

; #define PG8_STAGE(bufoff, gbase, voff) do { _Pragma("unroll") for (int _i = 0; _i < 2; ++_i) \
;         __builtin_amdgcn_global_load_lds((const unsigned*)((const char*)(gbase) + (voff)[_i]), (PG8_LAS unsigned*)(lds + (bufoff) + ldsw + _i * 8192), 16, 0, 0); } while (0)
; #define PG8_LDA(dst, b, h) do { _Pragma("unroll") for (int m = 0; m < 4; ++m) _Pragma("unroll") for (int k = 0; k < 2; ++k) dst[m][k] = *(const PG8_LAS bf16x8*)(lds + PG8_SA(b, h) + aoff + m * 2048 + k * 1024); } while (0)
; #define PG8_LDB(dst, b, h) do { _Pragma("unroll") for (int n = 0; n < 2; ++n) _Pragma("unroll") for (int k = 0; k < 2; ++k) dst[n][k] = *(const PG8_LAS bf16x8*)(lds + PG8_SB(b, h) + boff + n * 2048 + k * 1024); } while (0)
; #define PG8_MMA(ai, bj, At, Bt) do { __builtin_amdgcn_s_setprio(1); _Pragma("unroll") for (int m = 0; m < 4; ++m) _Pragma("unroll") for (int n = 0; n < 2; ++n) _Pragma("unroll") for (int k = 0; k < 2; ++k) \
;         acc[ai][bj][m][n] = __builtin_amdgcn_mfma_f32_16x16x32_bf16(Bt[n][k], At[m][k], acc[ai][bj][m][n], 0, 0, 0); __builtin_amdgcn_s_setprio(0); } while (0)
; #define PG8_WAIT_V(n) asm volatile("s_waitcnt vmcnt(" #n ")" ::: "memory")
; #define PG8_WAIT_L(n) asm volatile("s_waitcnt lgkmcnt(" #n ")" ::: "memory")
; #define PG8_BAR __builtin_amdgcn_s_barrier()
; #define PG8_SCHED __builtin_amdgcn_sched_barrier(0)
; template <class Epi, class Sched, bool ALIGN_EPI = false, bool SP2 = false>
; __device__ __forceinline__ void gemm_phase(PG8_LAS unsigned char* lds, const Gemm g, const Sched& S, const Epi& E) {
;     ...
;             PG8_LDB(B0, 0, 0); PG8_LDB(B1, 0, 1); PG8_SCHED; PG8_LDA(At, 0, 0); PG8_STAGE(PG8_SA(1, 1), a1 + hstep, voffA);
;             PG8_WAIT_V(8); PG8_WAIT_L(0); PG8_BAR; PG8_MMA(0, 0, At, B0); PG8_MMA(0, 1, At, B1); PG8_BAR; PG8_SCHED;
;             PG8_LDA(At, 0, 1); PG8_STAGE(PG8_SB(0, 0), b2, voffB); PG8_STAGE(PG8_SB(0, 1), b2 + hstep, voffB); PG8_STAGE(PG8_SA(0, 0), a2, voffA);
;             PG8_WAIT_V(8); PG8_WAIT_L(0); PG8_BAR; PG8_MMA(1, 0, At, B0); PG8_MMA(1, 1, At, B1); PG8_BAR; PG8_SCHED;
.Lpeel_g4:
	s_add_u32 s60, s58, 0x100
	s_addc_u32 s61, s59, 0
	s_add_i32 s5, 0, 0x10000
	s_cmp_eq_u32 s39, 40
	s_cselect_b32 s65, s1, s61
	s_cselect_b32 s64, s0, s60
	s_cselect_b32 s63, s57, s27
	s_cselect_b32 s62, s56, s26
	s_add_i32 s8, 0, 0x14000
	v_lshl_add_u64 v[214:215], s[58:59], 0, v[208:209]
	s_add_i32 m0, s67, 0xc000
	global_load_lds_dwordx4 v[214:215], off
	v_lshl_add_u64 v[214:215], s[58:59], 0, v[206:207]
	s_add_i32 m0, s67, 0xe000
	s_nop 0
	global_load_lds_dwordx4 v[214:215], off
	s_waitcnt vmcnt(32)
	s_waitcnt lgkmcnt(0)
	s_barrier
	s_setprio 1
	s_waitcnt lgkmcnt(0)
	v_mfma_f32_16x16x32_bf16 v[168:171], v[112:115], v[164:167], 0
	v_mfma_f32_16x16x32_bf16 v[160:163], v[120:123], v[164:167], 0
	v_mfma_f32_16x16x32_bf16 v[108:111], v[112:115], v[176:179], 0
	v_mfma_f32_16x16x32_bf16 v[104:107], v[120:123], v[176:179], 0
	v_mfma_f32_16x16x32_bf16 v[92:95], v[112:115], v[184:187], 0
	v_mfma_f32_16x16x32_bf16 v[88:91], v[120:123], v[184:187], 0
	v_mfma_f32_16x16x32_bf16 v[76:79], v[112:115], v[192:195], 0
	v_mfma_f32_16x16x32_bf16 v[72:75], v[120:123], v[192:195], 0
	v_mfma_f32_16x16x32_bf16 v[168:171], v[116:119], v[172:175], v[168:171]
	v_mfma_f32_16x16x32_bf16 v[160:163], v[124:127], v[172:175], v[160:163]
	v_mfma_f32_16x16x32_bf16 v[108:111], v[116:119], v[180:183], v[108:111]
	v_mfma_f32_16x16x32_bf16 v[104:107], v[124:127], v[180:183], v[104:107]
	v_mfma_f32_16x16x32_bf16 v[92:95], v[116:119], v[188:191], v[92:95]
	v_mfma_f32_16x16x32_bf16 v[88:91], v[124:127], v[188:191], v[88:91]
	v_mfma_f32_16x16x32_bf16 v[76:79], v[116:119], v[210:213], v[76:79]
	v_mfma_f32_16x16x32_bf16 v[72:75], v[124:127], v[210:213], v[72:75]
	s_setprio 0
	s_setprio 1
	v_mfma_f32_16x16x32_bf16 v[136:139], v[132:135], v[164:167], 0
	v_mfma_f32_16x16x32_bf16 v[128:131], v[152:155], v[164:167], 0
	v_mfma_f32_16x16x32_bf16 v[100:103], v[132:135], v[176:179], 0
	v_mfma_f32_16x16x32_bf16 v[96:99], v[152:155], v[176:179], 0
	v_mfma_f32_16x16x32_bf16 v[84:87], v[132:135], v[184:187], 0
	v_mfma_f32_16x16x32_bf16 v[80:83], v[152:155], v[184:187], 0
	v_mfma_f32_16x16x32_bf16 v[68:71], v[132:135], v[192:195], 0
	v_mfma_f32_16x16x32_bf16 v[64:67], v[152:155], v[192:195], 0
	v_mfma_f32_16x16x32_bf16 v[136:139], v[140:143], v[172:175], v[136:139]
	v_mfma_f32_16x16x32_bf16 v[128:131], v[156:159], v[172:175], v[128:131]
	v_mfma_f32_16x16x32_bf16 v[100:103], v[140:143], v[180:183], v[100:103]
	v_mfma_f32_16x16x32_bf16 v[96:99], v[156:159], v[180:183], v[96:99]
	v_mfma_f32_16x16x32_bf16 v[84:87], v[140:143], v[188:191], v[84:87]
	v_mfma_f32_16x16x32_bf16 v[80:83], v[156:159], v[188:191], v[80:83]
	v_mfma_f32_16x16x32_bf16 v[68:71], v[140:143], v[210:213], v[68:71]
	v_mfma_f32_16x16x32_bf16 v[64:67], v[156:159], v[210:213], v[64:67]
	s_setprio 0
	s_barrier
	s_add_i32 s5, s5, s66
	v_lshl_add_u64 v[214:215], s[62:63], 0, v[202:203]
	s_mov_b32 m0, s5
	ds_read_b128 v[164:167], v242 offset:16384
	ds_read_b128 v[172:175], v242 offset:17408
	ds_read_b128 v[176:179], v242 offset:18432
	ds_read_b128 v[180:183], v242 offset:19456
	ds_read_b128 v[184:187], v242 offset:20480
	ds_read_b128 v[188:191], v242 offset:21504
	ds_read_b128 v[192:195], v242 offset:22528
	ds_read_b128 v[210:213], v242 offset:23552
	global_load_lds_dwordx4 v[214:215], off
	s_add_i32 m0, s5, 0x2000
	s_add_u32 s20, s62, 0xb0000
	v_lshl_add_u64 v[216:217], s[62:63], 0, v[146:147]
	s_addc_u32 s21, s63, 0
	s_add_i32 s5, s8, s66
	global_load_lds_dwordx4 v[216:217], off
	v_lshl_add_u64 v[218:219], s[20:21], 0, v[202:203]
	s_mov_b32 m0, s5
	v_lshl_add_u64 v[220:221], s[64:65], 0, v[200:201]
	global_load_lds_dwordx4 v[218:219], off
	v_lshl_add_u64 v[218:219], s[20:21], 0, v[146:147]
	s_add_i32 m0, s5, 0x2000
	s_nop 0
	global_load_lds_dwordx4 v[218:219], off
	v_lshl_add_u64 v[218:219], s[64:65], 0, v[204:205]
	s_mov_b32 m0, s67
	s_nop 0
	global_load_lds_dwordx4 v[218:219], off
	s_mov_b32 m0, s68
	s_nop 0
	global_load_lds_dwordx4 v[220:221], off
	s_waitcnt vmcnt(32)
	s_waitcnt lgkmcnt(0)
	s_barrier
	s_setprio 1
	s_waitcnt lgkmcnt(0)
	v_mfma_f32_16x16x32_bf16 v[60:63], v[112:115], v[164:167], 0
	v_mfma_f32_16x16x32_bf16 v[56:59], v[120:123], v[164:167], 0
	v_mfma_f32_16x16x32_bf16 v[44:47], v[112:115], v[176:179], 0
	v_mfma_f32_16x16x32_bf16 v[40:43], v[120:123], v[176:179], 0
	v_mfma_f32_16x16x32_bf16 v[28:31], v[112:115], v[184:187], 0
	v_mfma_f32_16x16x32_bf16 v[24:27], v[120:123], v[184:187], 0
	v_mfma_f32_16x16x32_bf16 v[12:15], v[112:115], v[192:195], 0
	v_mfma_f32_16x16x32_bf16 v[8:11], v[120:123], v[192:195], 0
	v_mfma_f32_16x16x32_bf16 v[60:63], v[116:119], v[172:175], v[60:63]
	v_mfma_f32_16x16x32_bf16 v[56:59], v[124:127], v[172:175], v[56:59]
	v_mfma_f32_16x16x32_bf16 v[44:47], v[116:119], v[180:183], v[44:47]
	v_mfma_f32_16x16x32_bf16 v[40:43], v[124:127], v[180:183], v[40:43]
	v_mfma_f32_16x16x32_bf16 v[28:31], v[116:119], v[188:191], v[28:31]
	v_mfma_f32_16x16x32_bf16 v[24:27], v[124:127], v[188:191], v[24:27]
	v_mfma_f32_16x16x32_bf16 v[12:15], v[116:119], v[210:213], v[12:15]
	v_mfma_f32_16x16x32_bf16 v[8:11], v[124:127], v[210:213], v[8:11]
	s_setprio 0
	s_setprio 1
	v_mfma_f32_16x16x32_bf16 v[52:55], v[132:135], v[164:167], 0
	v_mfma_f32_16x16x32_bf16 v[48:51], v[152:155], v[164:167], 0
	v_mfma_f32_16x16x32_bf16 v[36:39], v[132:135], v[176:179], 0
	v_mfma_f32_16x16x32_bf16 v[32:35], v[152:155], v[176:179], 0
	v_mfma_f32_16x16x32_bf16 v[20:23], v[132:135], v[184:187], 0
	v_mfma_f32_16x16x32_bf16 v[16:19], v[152:155], v[184:187], 0
	v_mfma_f32_16x16x32_bf16 v[4:7], v[132:135], v[192:195], 0
	v_mfma_f32_16x16x32_bf16 v[0:3], v[152:155], v[192:195], 0
	v_mfma_f32_16x16x32_bf16 v[52:55], v[140:143], v[172:175], v[52:55]
	v_mfma_f32_16x16x32_bf16 v[48:51], v[156:159], v[172:175], v[48:51]
	v_mfma_f32_16x16x32_bf16 v[36:39], v[140:143], v[180:183], v[36:39]
	v_mfma_f32_16x16x32_bf16 v[32:35], v[156:159], v[180:183], v[32:35]
	v_mfma_f32_16x16x32_bf16 v[20:23], v[140:143], v[188:191], v[20:23]
	v_mfma_f32_16x16x32_bf16 v[16:19], v[156:159], v[188:191], v[16:19]
	v_mfma_f32_16x16x32_bf16 v[4:7], v[140:143], v[210:213], v[4:7]
	v_mfma_f32_16x16x32_bf16 v[0:3], v[156:159], v[210:213], v[0:3]
	s_setprio 0
	s_barrier
	s_branch .Lmid_g4

;     __device__ __forceinline__ void prefetch(Pre& p, const Unit& u, int wr, int fr, int fq) const { prefetch_ss(p, ss, u, wr, fr, fq); }
;     __device__ __forceinline__ void prefetch(Pre& p, const Unit& u, int wr, int fr, int fq) const { prefetch_ss(p, ss, u, wr, fr, fq); }
;     __device__ __forceinline__ void prefetch(Pre& p, const Unit& u, int wr, int fr, int fq) const { prefetch_ss(p, ss, u, wr, fr, fq); }
; #define PG8_STAGE(bufoff, gbase, voff) do { _Pragma("unroll") for (int _i = 0; _i < 2; ++_i) \
;         __builtin_amdgcn_global_load_lds((const unsigned*)((const char*)(gbase) + (voff)[_i]), (PG8_LAS unsigned*)(lds + (bufoff) + ldsw + _i * 8192), 16, 0, 0); } while (0)
; #define PG8_SCHED __builtin_amdgcn_sched_barrier(0)
;     __host__ __device__ bool next(int i, Unit& u) const {
;         const long L = (long)i * G + c; if (L >= nwg) return false;
;         int wgid = (int)L; { const int q = nwg / NXCD, r = nwg % NXCD, xcd = wgid % NXCD, off = wgid / NXCD; wgid = (xcd < r ? xcd * (q + 1) : r * (q + 1) + (xcd - r) * q) + off; }
;         const int nig = WGM * nN, gid = wgid / nig, fm = gid * WGM, gsz = (nM - fm) < WGM ? (nM - fm) : WGM;
;         u.pm = fm + ((wgid % nig) % gsz); u.pn = (wgid % nig) / gsz; return true;
;     }
; template <class Epi, class Sched, bool ALIGN_EPI = false, bool SP2 = false>
; __device__ __forceinline__ void gemm_phase(PG8_LAS unsigned char* lds, const Gemm g, const Sched& S, const Epi& E) {
;     ...
;         const bool has_next = S.next(ui + 1, nxt);
;         typename Epi::Pre pre; E.prefetch(pre, cur, wr, fr, fq);
;         const char* nA = has_next ? (const char*)g.A + (size_t)nxt.pm * tstep : cA; const char* nB = has_next ? (const char*)g.Bt + (size_t)nxt.pn * tstep : cB;
;         for (int t = 0; t < nt; t += 2) {
;             const bool last = (t == nt - 2);
;             const char* a1 = cA + (size_t)(t + 1) * kstep;
;             const char* a2 = last ? nA : cA + (size_t)(t + 2) * kstep; const char* b2 = last ? nB : cB + (size_t)(t + 2) * kstep;
;             const char* a3 = a2 + kstep; const char* b3 = b2 + kstep;
;             if (last && has_next) S.a_ready(nxt);
;             if constexpr (SP2) {
;             PG8_LDB(B0, 0, 0); PG8_LDB(B1, 0, 1); PG8_SCHED; PG8_LDA(At, 0, 0); PG8_STAGE(PG8_SA(1, 1), a1 + hstep, voffA);
.LBB0_149:
	s_add_i32 s71, s71, 1
	s_cmp_eq_u32 s71, 1
	s_cbranch_scc1 .Lnohoist_g3
	v_add_u32_e32 v143, 0x10000, v157
	ds_read_b128 v[162:165], v143
	ds_read_b128 v[166:169], v143 offset:1024
	ds_read_b128 v[170:173], v143 offset:2048
	ds_read_b128 v[174:177], v143 offset:3072
	v_add_u32_e32 v143, 0x14000, v157
	ds_read_b128 v[178:181], v143
	ds_read_b128 v[182:185], v143 offset:1024
	ds_read_b128 v[186:189], v143 offset:2048
	ds_read_b128 v[190:193], v143 offset:3072
	ds_read_b128 v[200:203], v161
	ds_read_b128 v[204:207], v161 offset:1024
	ds_read_b128 v[208:211], v161 offset:2048
	ds_read_b128 v[212:215], v161 offset:3072
	ds_read_b128 v[216:219], v161 offset:4096
	ds_read_b128 v[220:223], v161 offset:5120
	ds_read_b128 v[224:227], v161 offset:6144
	ds_read_b128 v[228:231], v161 offset:7168
.Lnohoist_g3:
	v_readlane_b32 s5, v252, 14
	s_mul_i32 s5, s71, s5
	s_mul_hi_u32 s8, s71, s9
	s_add_i32 s8, s8, s5
	s_mul_i32 s5, s71, s9
	s_add_u32 s26, s5, s76
	v_readlane_b32 s5, v254, 23
	s_addc_u32 s27, s8, s5
	v_mov_b64_e32 v[0:1], 0x1600
	v_cmp_lt_i64_e64 s[40:41], s[26:27], v[0:1]
	v_mov_b64_e32 v[0:1], 0x15ff
	v_cmp_gt_i64_e32 vcc, s[26:27], v[0:1]
	s_mov_b32 s8, s50
	s_cbranch_vccnz .LBB0_151
	s_ashr_i32 s5, s26, 31
	s_lshr_b32 s5, s5, 29
	s_add_i32 s5, s26, s5
	s_ashr_i32 s8, s5, 3
	s_and_b32 s5, s5, -8
	s_sub_i32 s5, s26, s5
	s_cmp_lt_i32 s5, 0
	s_movk_i32 s10, 0x2c1
	s_cselect_b32 s10, s10, 0x2c0
	s_mul_i32 s5, s5, s10
	s_add_i32 s5, s5, s8
	s_mul_hi_i32 s8, s5, 0x2e8ba2e9
	s_lshr_b32 s10, s8, 31
	s_ashr_i32 s8, s8, 5
	s_add_i32 s8, s8, s10
	s_lshl_b32 s10, s8, 3
	s_sub_i32 s12, 0x100, s10
	s_min_i32 s12, s12, 8
	s_cmp_lg_u32 s12, 8
	s_cbranch_scc1 .Lslowdiv_fd2
	s_mulk_i32 s8, 0xb0
	s_sub_i32 s5, s5, s8
	s_ashr_i32 s52, s5, 3
	s_and_b32 s5, s5, 7
	s_add_i32 s8, s10, s5
	s_branch .LBB0_151

; #define PG8_STAGE(bufoff, gbase, voff) do { _Pragma("unroll") for (int _i = 0; _i < 2; ++_i) \
;         __builtin_amdgcn_global_load_lds((const unsigned*)((const char*)(gbase) + (voff)[_i]), (PG8_LAS unsigned*)(lds + (bufoff) + ldsw + _i * 8192), 16, 0, 0); } while (0)
; #define PG8_LDA(dst, b, h) do { _Pragma("unroll") for (int m = 0; m < 4; ++m) _Pragma("unroll") for (int k = 0; k < 2; ++k) dst[m][k] = *(const PG8_LAS bf16x8*)(lds + PG8_SA(b, h) + aoff + m * 2048 + k * 1024); } while (0)
; #define PG8_LDB(dst, b, h) do { _Pragma("unroll") for (int n = 0; n < 2; ++n) _Pragma("unroll") for (int k = 0; k < 2; ++k) dst[n][k] = *(const PG8_LAS bf16x8*)(lds + PG8_SB(b, h) + boff + n * 2048 + k * 1024); } while (0)
; #define PG8_MMA(ai, bj, At, Bt) do { __builtin_amdgcn_s_setprio(1); _Pragma("unroll") for (int m = 0; m < 4; ++m) _Pragma("unroll") for (int n = 0; n < 2; ++n) _Pragma("unroll") for (int k = 0; k < 2; ++k) \
;         acc[ai][bj][m][n] = __builtin_amdgcn_mfma_f32_16x16x32_bf16(Bt[n][k], At[m][k], acc[ai][bj][m][n], 0, 0, 0); __builtin_amdgcn_s_setprio(0); } while (0)
; #define PG8_WAIT_V(n) asm volatile("s_waitcnt vmcnt(" #n ")" ::: "memory")
; #define PG8_WAIT_L(n) asm volatile("s_waitcnt lgkmcnt(" #n ")" ::: "memory")
; #define PG8_BAR __builtin_amdgcn_s_barrier()
; #define PG8_SCHED __builtin_amdgcn_sched_barrier(0)
; template <class Epi, class Sched, bool ALIGN_EPI = false, bool SP2 = false>
; __device__ __forceinline__ void gemm_phase(PG8_LAS unsigned char* lds, const Gemm g, const Sched& S, const Epi& E) {
;     ...
;             PG8_LDB(B0, 0, 0); PG8_LDB(B1, 0, 1); PG8_SCHED; PG8_LDA(At, 0, 0); PG8_STAGE(PG8_SA(1, 1), a1 + hstep, voffA);
;             PG8_WAIT_V(8); PG8_WAIT_L(0); PG8_BAR; PG8_MMA(0, 0, At, B0); PG8_MMA(0, 1, At, B1); PG8_BAR; PG8_SCHED;
;             PG8_LDA(At, 0, 1); PG8_STAGE(PG8_SB(0, 0), b2, voffB); PG8_STAGE(PG8_SB(0, 1), b2 + hstep, voffB); PG8_STAGE(PG8_SA(0, 0), a2, voffA);
;             PG8_WAIT_V(8); PG8_WAIT_L(0); PG8_BAR; PG8_MMA(1, 0, At, B0); PG8_MMA(1, 1, At, B1); PG8_BAR; PG8_SCHED;
.Lpeel_g3:
	s_add_u32 s5, s58, 0xfffc0080
	s_addc_u32 s8, s59, -1
	s_add_i32 s10, 0, 0x10000
	s_cmp_eq_u32 s72, 12
	s_cselect_b32 s63, s26, s8
	s_cselect_b32 s62, s27, s5
	s_cselect_b32 s61, s36, s53
	s_cselect_b32 s60, s39, s51
	s_add_i32 s5, 0, 0x14000
	v_lshl_add_u64 v[194:195], s[58:59], 0, v[140:141]
	s_add_i32 m0, s65, 0xc000
	global_load_lds_dwordx4 v[194:195], off
	v_lshl_add_u64 v[194:195], s[58:59], 0, v[138:139]
	s_add_i32 m0, s65, 0xe000
	s_nop 0
	global_load_lds_dwordx4 v[194:195], off
	s_waitcnt vmcnt(18)
	s_waitcnt lgkmcnt(0)
	s_barrier
	s_setprio 1
	s_waitcnt lgkmcnt(0)
	v_mfma_f32_16x16x32_bf16 v[124:127], v[162:165], v[200:203], 0
	v_mfma_f32_16x16x32_bf16 v[120:123], v[170:173], v[200:203], 0
	v_mfma_f32_16x16x32_bf16 v[108:111], v[162:165], v[208:211], 0
	v_mfma_f32_16x16x32_bf16 v[104:107], v[170:173], v[208:211], 0
	v_mfma_f32_16x16x32_bf16 v[92:95], v[162:165], v[216:219], 0
	v_mfma_f32_16x16x32_bf16 v[88:91], v[170:173], v[216:219], 0
	v_mfma_f32_16x16x32_bf16 v[76:79], v[162:165], v[224:227], 0
	v_mfma_f32_16x16x32_bf16 v[72:75], v[170:173], v[224:227], 0
	v_mfma_f32_16x16x32_bf16 v[124:127], v[166:169], v[204:207], v[124:127]
	v_mfma_f32_16x16x32_bf16 v[120:123], v[174:177], v[204:207], v[120:123]
	v_mfma_f32_16x16x32_bf16 v[108:111], v[166:169], v[212:215], v[108:111]
	v_mfma_f32_16x16x32_bf16 v[104:107], v[174:177], v[212:215], v[104:107]
	v_mfma_f32_16x16x32_bf16 v[92:95], v[166:169], v[220:223], v[92:95]
	v_mfma_f32_16x16x32_bf16 v[88:91], v[174:177], v[220:223], v[88:91]
	v_mfma_f32_16x16x32_bf16 v[76:79], v[166:169], v[228:231], v[76:79]
	v_mfma_f32_16x16x32_bf16 v[72:75], v[174:177], v[228:231], v[72:75]
	s_setprio 0
	s_setprio 1
	v_mfma_f32_16x16x32_bf16 v[116:119], v[178:181], v[200:203], 0
	v_mfma_f32_16x16x32_bf16 v[112:115], v[186:189], v[200:203], 0
	v_mfma_f32_16x16x32_bf16 v[100:103], v[178:181], v[208:211], 0
	v_mfma_f32_16x16x32_bf16 v[96:99], v[186:189], v[208:211], 0
	v_mfma_f32_16x16x32_bf16 v[84:87], v[178:181], v[216:219], 0
	v_mfma_f32_16x16x32_bf16 v[80:83], v[186:189], v[216:219], 0
	v_mfma_f32_16x16x32_bf16 v[68:71], v[178:181], v[224:227], 0
	v_mfma_f32_16x16x32_bf16 v[64:67], v[186:189], v[224:227], 0
	v_mfma_f32_16x16x32_bf16 v[116:119], v[182:185], v[204:207], v[116:119]
	v_mfma_f32_16x16x32_bf16 v[112:115], v[190:193], v[204:207], v[112:115]
	v_mfma_f32_16x16x32_bf16 v[100:103], v[182:185], v[212:215], v[100:103]
	v_mfma_f32_16x16x32_bf16 v[96:99], v[190:193], v[212:215], v[96:99]
	v_mfma_f32_16x16x32_bf16 v[84:87], v[182:185], v[220:223], v[84:87]
	v_mfma_f32_16x16x32_bf16 v[80:83], v[190:193], v[220:223], v[80:83]
	v_mfma_f32_16x16x32_bf16 v[68:71], v[182:185], v[228:231], v[68:71]
	v_mfma_f32_16x16x32_bf16 v[64:67], v[190:193], v[228:231], v[64:67]
	s_setprio 0
	s_barrier
	s_add_i32 s8, s10, s64
	v_lshl_add_u64 v[194:195], s[60:61], 0, v[132:133]
	s_mov_b32 m0, s8
	ds_read_b128 v[200:203], v161 offset:16384
	ds_read_b128 v[204:207], v161 offset:17408
	ds_read_b128 v[208:211], v161 offset:18432
	ds_read_b128 v[212:215], v161 offset:19456
	ds_read_b128 v[216:219], v161 offset:20480
	ds_read_b128 v[220:223], v161 offset:21504
	ds_read_b128 v[224:227], v161 offset:22528
	ds_read_b128 v[228:231], v161 offset:23552
	global_load_lds_dwordx4 v[194:195], off
	s_add_i32 m0, s8, 0x2000
	s_add_u32 s20, s60, 0x40000
	v_lshl_add_u64 v[240:241], s[60:61], 0, v[128:129]
	s_addc_u32 s21, s61, 0
	s_add_i32 s5, s5, s64
	global_load_lds_dwordx4 v[240:241], off
	v_lshl_add_u64 v[242:243], s[20:21], 0, v[132:133]
	s_mov_b32 m0, s5
	v_lshl_add_u64 v[244:245], s[62:63], 0, v[130:131]
	global_load_lds_dwordx4 v[242:243], off
	v_lshl_add_u64 v[242:243], s[20:21], 0, v[128:129]
	s_add_i32 m0, s5, 0x2000
	s_nop 0
	global_load_lds_dwordx4 v[242:243], off
	v_lshl_add_u64 v[242:243], s[62:63], 0, v[134:135]
	s_mov_b32 m0, s65
	s_nop 0
	global_load_lds_dwordx4 v[242:243], off
	s_mov_b32 m0, s66
	s_nop 0
	global_load_lds_dwordx4 v[244:245], off
	s_waitcnt vmcnt(18)
	s_waitcnt lgkmcnt(0)
	s_barrier
	s_setprio 1
	s_waitcnt lgkmcnt(0)
	v_mfma_f32_16x16x32_bf16 v[60:63], v[162:165], v[200:203], 0
	v_mfma_f32_16x16x32_bf16 v[56:59], v[170:173], v[200:203], 0
	v_mfma_f32_16x16x32_bf16 v[44:47], v[162:165], v[208:211], 0
	v_mfma_f32_16x16x32_bf16 v[40:43], v[170:173], v[208:211], 0
	v_mfma_f32_16x16x32_bf16 v[28:31], v[162:165], v[216:219], 0
	v_mfma_f32_16x16x32_bf16 v[24:27], v[170:173], v[216:219], 0
	v_mfma_f32_16x16x32_bf16 v[12:15], v[162:165], v[224:227], 0
	v_mfma_f32_16x16x32_bf16 v[8:11], v[170:173], v[224:227], 0
	v_mfma_f32_16x16x32_bf16 v[60:63], v[166:169], v[204:207], v[60:63]
	v_mfma_f32_16x16x32_bf16 v[56:59], v[174:177], v[204:207], v[56:59]
	v_mfma_f32_16x16x32_bf16 v[44:47], v[166:169], v[212:215], v[44:47]
	v_mfma_f32_16x16x32_bf16 v[40:43], v[174:177], v[212:215], v[40:43]
	v_mfma_f32_16x16x32_bf16 v[28:31], v[166:169], v[220:223], v[28:31]
	v_mfma_f32_16x16x32_bf16 v[24:27], v[174:177], v[220:223], v[24:27]
	v_mfma_f32_16x16x32_bf16 v[12:15], v[166:169], v[228:231], v[12:15]
	v_mfma_f32_16x16x32_bf16 v[8:11], v[174:177], v[228:231], v[8:11]
	s_setprio 0
	s_setprio 1
	v_mfma_f32_16x16x32_bf16 v[52:55], v[178:181], v[200:203], 0
	v_mfma_f32_16x16x32_bf16 v[48:51], v[186:189], v[200:203], 0
	v_mfma_f32_16x16x32_bf16 v[36:39], v[178:181], v[208:211], 0
	v_mfma_f32_16x16x32_bf16 v[32:35], v[186:189], v[208:211], 0
	v_mfma_f32_16x16x32_bf16 v[20:23], v[178:181], v[216:219], 0
	v_mfma_f32_16x16x32_bf16 v[16:19], v[186:189], v[216:219], 0
	v_mfma_f32_16x16x32_bf16 v[4:7], v[178:181], v[224:227], 0
	v_mfma_f32_16x16x32_bf16 v[0:3], v[186:189], v[224:227], 0
	v_mfma_f32_16x16x32_bf16 v[52:55], v[182:185], v[204:207], v[52:55]
	v_mfma_f32_16x16x32_bf16 v[48:51], v[190:193], v[204:207], v[48:51]
	v_mfma_f32_16x16x32_bf16 v[36:39], v[182:185], v[212:215], v[36:39]
	v_mfma_f32_16x16x32_bf16 v[32:35], v[190:193], v[212:215], v[32:35]
	v_mfma_f32_16x16x32_bf16 v[20:23], v[182:185], v[220:223], v[20:23]
	v_mfma_f32_16x16x32_bf16 v[16:19], v[190:193], v[220:223], v[16:19]
	v_mfma_f32_16x16x32_bf16 v[4:7], v[182:185], v[228:231], v[4:7]
	v_mfma_f32_16x16x32_bf16 v[0:3], v[190:193], v[228:231], v[0:3]
	s_setprio 0
	s_barrier
	s_branch .Lmid_g3

;     __device__ __forceinline__ void prefetch(Pre& p, const Unit& u, int wr, int fr, int fq) const { prefetch_ss(p, ss, u, wr, fr, fq); }
;     __device__ __forceinline__ void prefetch(Pre& p, const Unit& u, int wr, int fr, int fq) const { prefetch_ss(p, ss, u, wr, fr, fq); }
;     __device__ __forceinline__ void prefetch(Pre& p, const Unit& u, int wr, int fr, int fq) const { prefetch_ss(p, ss, u, wr, fr, fq); }
; #define PG8_STAGE(bufoff, gbase, voff) do { _Pragma("unroll") for (int _i = 0; _i < 2; ++_i) \
;         __builtin_amdgcn_global_load_lds((const unsigned*)((const char*)(gbase) + (voff)[_i]), (PG8_LAS unsigned*)(lds + (bufoff) + ldsw + _i * 8192), 16, 0, 0); } while (0)
; #define PG8_SCHED __builtin_amdgcn_sched_barrier(0)
;     __host__ __device__ bool next(int i, Unit& u) const {
;         const long L = (long)i * G + c; if (L >= nwg) return false;
;         int wgid = (int)L; { const int q = nwg / NXCD, r = nwg % NXCD, xcd = wgid % NXCD, off = wgid / NXCD; wgid = (xcd < r ? xcd * (q + 1) : r * (q + 1) + (xcd - r) * q) + off; }
;         const int nig = WGM * nN, gid = wgid / nig, fm = gid * WGM, gsz = (nM - fm) < WGM ? (nM - fm) : WGM;
;         u.pm = fm + ((wgid % nig) % gsz); u.pn = (wgid % nig) / gsz; return true;
;     }
; template <class Epi, class Sched, bool ALIGN_EPI = false, bool SP2 = false>
; __device__ __forceinline__ void gemm_phase(PG8_LAS unsigned char* lds, const Gemm g, const Sched& S, const Epi& E) {
;     ...
;         const bool has_next = S.next(ui + 1, nxt);
;         typename Epi::Pre pre; E.prefetch(pre, cur, wr, fr, fq);
;         const char* nA = has_next ? (const char*)g.A + (size_t)nxt.pm * tstep : cA; const char* nB = has_next ? (const char*)g.Bt + (size_t)nxt.pn * tstep : cB;
;         for (int t = 0; t < nt; t += 2) {
;             const bool last = (t == nt - 2);
;             const char* a1 = cA + (size_t)(t + 1) * kstep;
;             const char* a2 = last ? nA : cA + (size_t)(t + 2) * kstep; const char* b2 = last ? nB : cB + (size_t)(t + 2) * kstep;
;             const char* a3 = a2 + kstep; const char* b3 = b2 + kstep;
;             if (last && has_next) S.a_ready(nxt);
;             if constexpr (SP2) {
;             PG8_LDB(B0, 0, 0); PG8_LDB(B1, 0, 1); PG8_SCHED; PG8_LDA(At, 0, 0); PG8_STAGE(PG8_SA(1, 1), a1 + hstep, voffA);
.LBB0_167:
	s_add_i32 s72, s72, 1
	v_readlane_b32 s5, v252, 14
	s_mul_i32 s5, s72, s5
	s_mul_hi_u32 s8, s72, s9
	s_add_i32 s8, s8, s5
	s_mul_i32 s5, s72, s9
	s_add_u32 s26, s5, s76
	v_readlane_b32 s5, v254, 23
	s_addc_u32 s27, s8, s5
	s_waitcnt lgkmcnt(0)
	s_cmp_eq_u32 s72, 1
	s_cbranch_scc1 .Lnohoist_g2
	v_add_u32_e32 v124, 0x10000, v240
	v_add_u32_e32 v156, 0x14000, v240
	ds_read_b128 v[112:115], v124
	ds_read_b128 v[116:119], v124 offset:1024
	ds_read_b128 v[120:123], v124 offset:2048
	ds_read_b128 v[124:127], v124 offset:3072
	ds_read_b128 v[136:139], v156
	ds_read_b128 v[140:143], v156 offset:1024
	ds_read_b128 v[152:155], v156 offset:2048
	ds_read_b128 v[156:159], v156 offset:3072
	ds_read_b128 v[164:167], v242
	ds_read_b128 v[172:175], v242 offset:1024
	ds_read_b128 v[176:179], v242 offset:2048
	ds_read_b128 v[180:183], v242 offset:3072
	ds_read_b128 v[184:187], v242 offset:4096
	ds_read_b128 v[188:191], v242 offset:5120
	ds_read_b128 v[192:195], v242 offset:6144
	ds_read_b128 v[210:213], v242 offset:7168
.Lnohoist_g2:
	v_mov_b64_e32 v[0:1], 0x3ff
	v_cmp_gt_i64_e32 vcc, s[26:27], v[0:1]
	v_cmp_lt_i64_e64 s[42:43], s[26:27], v[198:199]
	s_cbranch_vccnz .LBB0_173
	s_ashr_i32 s5, s26, 31
	s_lshr_b32 s5, s5, 29
	s_add_i32 s8, s26, s5
	s_and_b32 s5, s8, -8
	s_sub_i32 s10, s26, s5
	s_cmp_gt_i32 s10, -1
	s_mov_b64 s[26:27], -1
	s_cbranch_scc0 .LBB0_170
	s_lshl_b32 s12, s10, 7
	s_mov_b64 s[26:27], 0

; #define PG8_STAGE(bufoff, gbase, voff) do { _Pragma("unroll") for (int _i = 0; _i < 2; ++_i) \
;         __builtin_amdgcn_global_load_lds((const unsigned*)((const char*)(gbase) + (voff)[_i]), (PG8_LAS unsigned*)(lds + (bufoff) + ldsw + _i * 8192), 16, 0, 0); } while (0)
; #define PG8_LDA(dst, b, h) do { _Pragma("unroll") for (int m = 0; m < 4; ++m) _Pragma("unroll") for (int k = 0; k < 2; ++k) dst[m][k] = *(const PG8_LAS bf16x8*)(lds + PG8_SA(b, h) + aoff + m * 2048 + k * 1024); } while (0)
; #define PG8_LDB(dst, b, h) do { _Pragma("unroll") for (int n = 0; n < 2; ++n) _Pragma("unroll") for (int k = 0; k < 2; ++k) dst[n][k] = *(const PG8_LAS bf16x8*)(lds + PG8_SB(b, h) + boff + n * 2048 + k * 1024); } while (0)
; #define PG8_MMA(ai, bj, At, Bt) do { __builtin_amdgcn_s_setprio(1); _Pragma("unroll") for (int m = 0; m < 4; ++m) _Pragma("unroll") for (int n = 0; n < 2; ++n) _Pragma("unroll") for (int k = 0; k < 2; ++k) \
;         acc[ai][bj][m][n] = __builtin_amdgcn_mfma_f32_16x16x32_bf16(Bt[n][k], At[m][k], acc[ai][bj][m][n], 0, 0, 0); __builtin_amdgcn_s_setprio(0); } while (0)
; #define PG8_WAIT_V(n) asm volatile("s_waitcnt vmcnt(" #n ")" ::: "memory")
; #define PG8_WAIT_L(n) asm volatile("s_waitcnt lgkmcnt(" #n ")" ::: "memory")
; #define PG8_BAR __builtin_amdgcn_s_barrier()
; #define PG8_SCHED __builtin_amdgcn_sched_barrier(0)
; template <class Epi, class Sched, bool ALIGN_EPI = false, bool SP2 = false>
; __device__ __forceinline__ void gemm_phase(PG8_LAS unsigned char* lds, const Gemm g, const Sched& S, const Epi& E) {
;     ...
;             PG8_LDB(B0, 0, 0); PG8_LDB(B1, 0, 1); PG8_SCHED; PG8_LDA(At, 0, 0); PG8_STAGE(PG8_SA(1, 1), a1 + hstep, voffA);
;             PG8_WAIT_V(8); PG8_WAIT_L(0); PG8_BAR; PG8_MMA(0, 0, At, B0); PG8_MMA(0, 1, At, B1); PG8_BAR; PG8_SCHED;
;             PG8_LDA(At, 0, 1); PG8_STAGE(PG8_SB(0, 0), b2, voffB); PG8_STAGE(PG8_SB(0, 1), b2 + hstep, voffB); PG8_STAGE(PG8_SA(0, 0), a2, voffA);
;             PG8_WAIT_V(8); PG8_WAIT_L(0); PG8_BAR; PG8_MMA(1, 0, At, B0); PG8_MMA(1, 1, At, B1); PG8_BAR; PG8_SCHED;
.Lpeel_g2:
	s_add_u32 s5, s60, 0xfffc0080
	s_addc_u32 s8, s61, -1
	s_add_i32 s10, 0, 0x10000
	s_cmp_eq_u32 s74, 12
	s_cselect_b32 s65, s26, s8
	s_cselect_b32 s64, s27, s5
	s_cselect_b32 s63, s39, s73
	s_cselect_b32 s62, s53, s55
	s_add_i32 s5, 0, 0x14000
	v_lshl_add_u64 v[214:215], s[60:61], 0, v[208:209]
	s_add_i32 m0, s67, 0xc000
	global_load_lds_dwordx4 v[214:215], off
	v_lshl_add_u64 v[214:215], s[60:61], 0, v[206:207]
	s_add_i32 m0, s67, 0xe000
	s_nop 0
	global_load_lds_dwordx4 v[214:215], off
	s_waitcnt vmcnt(32)
	s_waitcnt lgkmcnt(0)
	s_barrier
	s_setprio 1
	s_waitcnt lgkmcnt(0)
	v_mfma_f32_16x16x32_bf16 v[168:171], v[112:115], v[164:167], 0
	v_mfma_f32_16x16x32_bf16 v[160:163], v[120:123], v[164:167], 0
	v_mfma_f32_16x16x32_bf16 v[108:111], v[112:115], v[176:179], 0
	v_mfma_f32_16x16x32_bf16 v[104:107], v[120:123], v[176:179], 0
	v_mfma_f32_16x16x32_bf16 v[92:95], v[112:115], v[184:187], 0
	v_mfma_f32_16x16x32_bf16 v[88:91], v[120:123], v[184:187], 0
	v_mfma_f32_16x16x32_bf16 v[76:79], v[112:115], v[192:195], 0
	v_mfma_f32_16x16x32_bf16 v[72:75], v[120:123], v[192:195], 0
	v_mfma_f32_16x16x32_bf16 v[168:171], v[116:119], v[172:175], v[168:171]
	v_mfma_f32_16x16x32_bf16 v[160:163], v[124:127], v[172:175], v[160:163]
	v_mfma_f32_16x16x32_bf16 v[108:111], v[116:119], v[180:183], v[108:111]
	v_mfma_f32_16x16x32_bf16 v[104:107], v[124:127], v[180:183], v[104:107]
	v_mfma_f32_16x16x32_bf16 v[92:95], v[116:119], v[188:191], v[92:95]
	v_mfma_f32_16x16x32_bf16 v[88:91], v[124:127], v[188:191], v[88:91]
	v_mfma_f32_16x16x32_bf16 v[76:79], v[116:119], v[210:213], v[76:79]
	v_mfma_f32_16x16x32_bf16 v[72:75], v[124:127], v[210:213], v[72:75]
	s_setprio 0
	s_setprio 1
	v_mfma_f32_16x16x32_bf16 v[132:135], v[136:139], v[164:167], 0
	v_mfma_f32_16x16x32_bf16 v[128:131], v[152:155], v[164:167], 0
	v_mfma_f32_16x16x32_bf16 v[100:103], v[136:139], v[176:179], 0
	v_mfma_f32_16x16x32_bf16 v[96:99], v[152:155], v[176:179], 0
	v_mfma_f32_16x16x32_bf16 v[84:87], v[136:139], v[184:187], 0
	v_mfma_f32_16x16x32_bf16 v[80:83], v[152:155], v[184:187], 0
	v_mfma_f32_16x16x32_bf16 v[68:71], v[136:139], v[192:195], 0
	v_mfma_f32_16x16x32_bf16 v[64:67], v[152:155], v[192:195], 0
	v_mfma_f32_16x16x32_bf16 v[132:135], v[140:143], v[172:175], v[132:135]
	v_mfma_f32_16x16x32_bf16 v[128:131], v[156:159], v[172:175], v[128:131]
	v_mfma_f32_16x16x32_bf16 v[100:103], v[140:143], v[180:183], v[100:103]
	v_mfma_f32_16x16x32_bf16 v[96:99], v[156:159], v[180:183], v[96:99]
	v_mfma_f32_16x16x32_bf16 v[84:87], v[140:143], v[188:191], v[84:87]
	v_mfma_f32_16x16x32_bf16 v[80:83], v[156:159], v[188:191], v[80:83]
	v_mfma_f32_16x16x32_bf16 v[68:71], v[140:143], v[210:213], v[68:71]
	v_mfma_f32_16x16x32_bf16 v[64:67], v[156:159], v[210:213], v[64:67]
	s_setprio 0
	s_barrier
	s_add_i32 s8, s10, s66
	v_lshl_add_u64 v[214:215], s[62:63], 0, v[202:203]
	s_mov_b32 m0, s8
	ds_read_b128 v[164:167], v242 offset:16384
	ds_read_b128 v[172:175], v242 offset:17408
	ds_read_b128 v[176:179], v242 offset:18432
	ds_read_b128 v[180:183], v242 offset:19456
	ds_read_b128 v[184:187], v242 offset:20480
	ds_read_b128 v[188:191], v242 offset:21504
	ds_read_b128 v[192:195], v242 offset:22528
	ds_read_b128 v[210:213], v242 offset:23552
	global_load_lds_dwordx4 v[214:215], off
	s_add_i32 m0, s8, 0x2000
	s_add_u32 s20, s62, 0x40000
	v_lshl_add_u64 v[216:217], s[62:63], 0, v[146:147]
	s_addc_u32 s21, s63, 0
	s_add_i32 s5, s5, s66
	global_load_lds_dwordx4 v[216:217], off
	v_lshl_add_u64 v[218:219], s[20:21], 0, v[202:203]
	s_mov_b32 m0, s5
	v_lshl_add_u64 v[220:221], s[64:65], 0, v[200:201]
	global_load_lds_dwordx4 v[218:219], off
	v_lshl_add_u64 v[218:219], s[20:21], 0, v[146:147]
	s_add_i32 m0, s5, 0x2000
	s_nop 0
	global_load_lds_dwordx4 v[218:219], off
	v_lshl_add_u64 v[218:219], s[64:65], 0, v[204:205]
	s_mov_b32 m0, s67
	s_nop 0
	global_load_lds_dwordx4 v[218:219], off
	s_mov_b32 m0, s68
	s_nop 0
	global_load_lds_dwordx4 v[220:221], off
	s_waitcnt vmcnt(32)
	s_waitcnt lgkmcnt(0)
	s_barrier
	s_setprio 1
	s_waitcnt lgkmcnt(0)
	v_mfma_f32_16x16x32_bf16 v[60:63], v[112:115], v[164:167], 0
	v_mfma_f32_16x16x32_bf16 v[56:59], v[120:123], v[164:167], 0
	v_mfma_f32_16x16x32_bf16 v[44:47], v[112:115], v[176:179], 0
	v_mfma_f32_16x16x32_bf16 v[40:43], v[120:123], v[176:179], 0
	v_mfma_f32_16x16x32_bf16 v[28:31], v[112:115], v[184:187], 0
	v_mfma_f32_16x16x32_bf16 v[24:27], v[120:123], v[184:187], 0
	v_mfma_f32_16x16x32_bf16 v[12:15], v[112:115], v[192:195], 0
	v_mfma_f32_16x16x32_bf16 v[8:11], v[120:123], v[192:195], 0
	v_mfma_f32_16x16x32_bf16 v[60:63], v[116:119], v[172:175], v[60:63]
	v_mfma_f32_16x16x32_bf16 v[56:59], v[124:127], v[172:175], v[56:59]
	v_mfma_f32_16x16x32_bf16 v[44:47], v[116:119], v[180:183], v[44:47]
	v_mfma_f32_16x16x32_bf16 v[40:43], v[124:127], v[180:183], v[40:43]
	v_mfma_f32_16x16x32_bf16 v[28:31], v[116:119], v[188:191], v[28:31]
	v_mfma_f32_16x16x32_bf16 v[24:27], v[124:127], v[188:191], v[24:27]
	v_mfma_f32_16x16x32_bf16 v[12:15], v[116:119], v[210:213], v[12:15]
	v_mfma_f32_16x16x32_bf16 v[8:11], v[124:127], v[210:213], v[8:11]
	s_setprio 0
	s_setprio 1
	v_mfma_f32_16x16x32_bf16 v[52:55], v[136:139], v[164:167], 0
	v_mfma_f32_16x16x32_bf16 v[48:51], v[152:155], v[164:167], 0
	v_mfma_f32_16x16x32_bf16 v[36:39], v[136:139], v[176:179], 0
	v_mfma_f32_16x16x32_bf16 v[32:35], v[152:155], v[176:179], 0
	v_mfma_f32_16x16x32_bf16 v[20:23], v[136:139], v[184:187], 0
	v_mfma_f32_16x16x32_bf16 v[16:19], v[152:155], v[184:187], 0
	v_mfma_f32_16x16x32_bf16 v[4:7], v[136:139], v[192:195], 0
	v_mfma_f32_16x16x32_bf16 v[0:3], v[152:155], v[192:195], 0
	v_mfma_f32_16x16x32_bf16 v[52:55], v[140:143], v[172:175], v[52:55]
	v_mfma_f32_16x16x32_bf16 v[48:51], v[156:159], v[172:175], v[48:51]
	v_mfma_f32_16x16x32_bf16 v[36:39], v[140:143], v[180:183], v[36:39]
	v_mfma_f32_16x16x32_bf16 v[32:35], v[156:159], v[180:183], v[32:35]
	v_mfma_f32_16x16x32_bf16 v[20:23], v[140:143], v[188:191], v[20:23]
	v_mfma_f32_16x16x32_bf16 v[16:19], v[156:159], v[188:191], v[16:19]
	v_mfma_f32_16x16x32_bf16 v[4:7], v[140:143], v[210:213], v[4:7]
	v_mfma_f32_16x16x32_bf16 v[0:3], v[156:159], v[210:213], v[0:3]
	s_setprio 0
	s_barrier
	s_branch .Lmid_g2

;     __device__ __forceinline__ void prefetch(Pre& p, const Unit& u, int wr, int fr, int fq) const { prefetch_ss(p, ss, u, wr, fr, fq); }
;     __device__ __forceinline__ void prefetch(Pre& p, const Unit& u, int wr, int fr, int fq) const { prefetch_ss(p, ss, u, wr, fr, fq); }
;     __device__ __forceinline__ void prefetch(Pre& p, const Unit& u, int wr, int fr, int fq) const { prefetch_ss(p, ss, u, wr, fr, fq); }
; #define PG8_STAGE(bufoff, gbase, voff) do { _Pragma("unroll") for (int _i = 0; _i < 2; ++_i) \
;         __builtin_amdgcn_global_load_lds((const unsigned*)((const char*)(gbase) + (voff)[_i]), (PG8_LAS unsigned*)(lds + (bufoff) + ldsw + _i * 8192), 16, 0, 0); } while (0)
; #define PG8_SCHED __builtin_amdgcn_sched_barrier(0)
;     __host__ __device__ bool next(int i, Unit& u) const {
;         const long L = (long)i * G + c; if (L >= nwg) return false;
;         int wgid = (int)L; { const int q = nwg / NXCD, r = nwg % NXCD, xcd = wgid % NXCD, off = wgid / NXCD; wgid = (xcd < r ? xcd * (q + 1) : r * (q + 1) + (xcd - r) * q) + off; }
;         const int nig = WGM * nN, gid = wgid / nig, fm = gid * WGM, gsz = (nM - fm) < WGM ? (nM - fm) : WGM;
;         u.pm = fm + ((wgid % nig) % gsz); u.pn = (wgid % nig) / gsz; return true;
;     }
; template <class Epi, class Sched, bool ALIGN_EPI = false, bool SP2 = false>
; __device__ __forceinline__ void gemm_phase(PG8_LAS unsigned char* lds, const Gemm g, const Sched& S, const Epi& E) {
;     ...
;         const bool has_next = S.next(ui + 1, nxt);
;         typename Epi::Pre pre; E.prefetch(pre, cur, wr, fr, fq);
;         const char* nA = has_next ? (const char*)g.A + (size_t)nxt.pm * tstep : cA; const char* nB = has_next ? (const char*)g.Bt + (size_t)nxt.pn * tstep : cB;
;         for (int t = 0; t < nt; t += 2) {
;             const bool last = (t == nt - 2);
;             const char* a1 = cA + (size_t)(t + 1) * kstep;
;             const char* a2 = last ? nA : cA + (size_t)(t + 2) * kstep; const char* b2 = last ? nB : cB + (size_t)(t + 2) * kstep;
;             const char* a3 = a2 + kstep; const char* b3 = b2 + kstep;
;             if (last && has_next) S.a_ready(nxt);
;             if constexpr (SP2) {
;             PG8_LDB(B0, 0, 0); PG8_LDB(B1, 0, 1); PG8_SCHED; PG8_LDA(At, 0, 0); PG8_STAGE(PG8_SA(1, 1), a1 + hstep, voffA);
.LBB0_407:
	s_add_i32 s66, s66, 1
	s_cmp_eq_u32 s66, 1
	s_cbranch_scc1 .Lnohoist_g1e
	v_add_u32_e32 v154, 0x10000, v157
	ds_read_b128 v[162:165], v154
	ds_read_b128 v[166:169], v154 offset:1024
	ds_read_b128 v[170:173], v154 offset:2048
	ds_read_b128 v[174:177], v154 offset:3072
	v_add_u32_e32 v154, 0x14000, v157
	ds_read_b128 v[178:181], v154
	ds_read_b128 v[182:185], v154 offset:1024
	ds_read_b128 v[186:189], v154 offset:2048
	ds_read_b128 v[190:193], v154 offset:3072
	ds_read_b128 v[200:203], v161
	ds_read_b128 v[204:207], v161 offset:1024
	ds_read_b128 v[208:211], v161 offset:2048
	ds_read_b128 v[212:215], v161 offset:3072
	ds_read_b128 v[216:219], v161 offset:4096
	ds_read_b128 v[220:223], v161 offset:5120
	ds_read_b128 v[224:227], v161 offset:6144
	ds_read_b128 v[228:231], v161 offset:7168
.Lnohoist_g1e:
	v_readlane_b32 s4, v252, 14
	s_mul_i32 s4, s66, s4
	s_mul_hi_u32 s8, s66, s9
	s_add_i32 s8, s8, s4
	s_mul_i32 s4, s66, s9
	s_lshl_b32 s26, s66, 5
	s_and_b32 s26, s26, 0x80
	s_cmp_eq_u32 s9, 0x100
	s_cselect_b32 s26, s26, 0
	s_xor_b32 s26, s26, s76
	s_add_u32 s26, s4, s26
	v_readlane_b32 s4, v254, 23
	s_addc_u32 s27, s8, s4
	v_mov_b64_e32 v[0:1], 0x1000
	v_cmp_lt_i64_e64 s[42:43], s[26:27], v[0:1]
	v_mov_b64_e32 v[0:1], 0xfff
	v_cmp_gt_i64_e32 vcc, s[26:27], v[0:1]
	s_cbranch_vccnz .LBB0_413
	s_ashr_i32 s4, s26, 31
	s_lshr_b32 s4, s4, 29
	s_add_i32 s4, s26, s4
	s_and_b32 s8, s4, -8
	s_sub_i32 s8, s26, s8
	s_cmp_gt_i32 s8, -1
	s_mov_b64 s[26:27], -1
	s_cbranch_scc0 .LBB0_410
	s_lshl_b32 s10, s8, 9
	s_mov_b64 s[26:27], 0

; #define PG8_STAGE(bufoff, gbase, voff) do { _Pragma("unroll") for (int _i = 0; _i < 2; ++_i) \
;         __builtin_amdgcn_global_load_lds((const unsigned*)((const char*)(gbase) + (voff)[_i]), (PG8_LAS unsigned*)(lds + (bufoff) + ldsw + _i * 8192), 16, 0, 0); } while (0)
; #define PG8_LDA(dst, b, h) do { _Pragma("unroll") for (int m = 0; m < 4; ++m) _Pragma("unroll") for (int k = 0; k < 2; ++k) dst[m][k] = *(const PG8_LAS bf16x8*)(lds + PG8_SA(b, h) + aoff + m * 2048 + k * 1024); } while (0)
; #define PG8_LDB(dst, b, h) do { _Pragma("unroll") for (int n = 0; n < 2; ++n) _Pragma("unroll") for (int k = 0; k < 2; ++k) dst[n][k] = *(const PG8_LAS bf16x8*)(lds + PG8_SB(b, h) + boff + n * 2048 + k * 1024); } while (0)
; #define PG8_MMA(ai, bj, At, Bt) do { __builtin_amdgcn_s_setprio(1); _Pragma("unroll") for (int m = 0; m < 4; ++m) _Pragma("unroll") for (int n = 0; n < 2; ++n) _Pragma("unroll") for (int k = 0; k < 2; ++k) \
;         acc[ai][bj][m][n] = __builtin_amdgcn_mfma_f32_16x16x32_bf16(Bt[n][k], At[m][k], acc[ai][bj][m][n], 0, 0, 0); __builtin_amdgcn_s_setprio(0); } while (0)
; #define PG8_WAIT_V(n) asm volatile("s_waitcnt vmcnt(" #n ")" ::: "memory")
; #define PG8_WAIT_L(n) asm volatile("s_waitcnt lgkmcnt(" #n ")" ::: "memory")
; #define PG8_BAR __builtin_amdgcn_s_barrier()
; #define PG8_SCHED __builtin_amdgcn_sched_barrier(0)
; template <class Epi, class Sched, bool ALIGN_EPI = false, bool SP2 = false>
; __device__ __forceinline__ void gemm_phase(PG8_LAS unsigned char* lds, const Gemm g, const Sched& S, const Epi& E) {
;     ...
;             PG8_LDB(B0, 0, 0); PG8_LDB(B1, 0, 1); PG8_SCHED; PG8_LDA(At, 0, 0); PG8_STAGE(PG8_SA(1, 1), a1 + hstep, voffA);
;             PG8_WAIT_V(8); PG8_WAIT_L(0); PG8_BAR; PG8_MMA(0, 0, At, B0); PG8_MMA(0, 1, At, B1); PG8_BAR; PG8_SCHED;
;             PG8_LDA(At, 0, 1); PG8_STAGE(PG8_SB(0, 0), b2, voffB); PG8_STAGE(PG8_SB(0, 1), b2 + hstep, voffB); PG8_STAGE(PG8_SA(0, 0), a2, voffA);
;             PG8_WAIT_V(8); PG8_WAIT_L(0); PG8_BAR; PG8_MMA(1, 0, At, B0); PG8_MMA(1, 1, At, B1); PG8_BAR; PG8_SCHED;
.Lpeel_g1e:
	s_add_u32 s8, s44, 0xfffc0080
	s_addc_u32 s10, s45, -1
	s_add_i32 s12, 0, 0x10000
	s_cmp_eq_u32 s69, 12
	s_cselect_b32 s57, s4, s10
	s_cselect_b32 s56, s26, s8
	s_cselect_b32 s55, s27, s49
	s_cselect_b32 s54, s36, s47
	s_add_i32 s8, 0, 0x14000
	v_lshl_add_u64 v[194:195], s[44:45], 0, v[140:141]
	s_add_i32 m0, s58, 0xc000
	global_load_lds_dwordx4 v[194:195], off
	v_lshl_add_u64 v[194:195], s[44:45], 0, v[138:139]
	s_add_i32 m0, s58, 0xe000
	s_nop 0
	global_load_lds_dwordx4 v[194:195], off
	s_waitcnt vmcnt(26)
	s_waitcnt lgkmcnt(0)
	s_barrier
	s_setprio 1
	s_waitcnt lgkmcnt(0)
	v_mfma_f32_16x16x32_bf16 v[124:127], v[162:165], v[200:203], 0
	v_mfma_f32_16x16x32_bf16 v[120:123], v[170:173], v[200:203], 0
	v_mfma_f32_16x16x32_bf16 v[108:111], v[162:165], v[208:211], 0
	v_mfma_f32_16x16x32_bf16 v[104:107], v[170:173], v[208:211], 0
	v_mfma_f32_16x16x32_bf16 v[92:95], v[162:165], v[216:219], 0
	v_mfma_f32_16x16x32_bf16 v[88:91], v[170:173], v[216:219], 0
	v_mfma_f32_16x16x32_bf16 v[76:79], v[162:165], v[224:227], 0
	v_mfma_f32_16x16x32_bf16 v[72:75], v[170:173], v[224:227], 0
	v_mfma_f32_16x16x32_bf16 v[124:127], v[166:169], v[204:207], v[124:127]
	v_mfma_f32_16x16x32_bf16 v[120:123], v[174:177], v[204:207], v[120:123]
	v_mfma_f32_16x16x32_bf16 v[108:111], v[166:169], v[212:215], v[108:111]
	v_mfma_f32_16x16x32_bf16 v[104:107], v[174:177], v[212:215], v[104:107]
	v_mfma_f32_16x16x32_bf16 v[92:95], v[166:169], v[220:223], v[92:95]
	v_mfma_f32_16x16x32_bf16 v[88:91], v[174:177], v[220:223], v[88:91]
	v_mfma_f32_16x16x32_bf16 v[76:79], v[166:169], v[228:231], v[76:79]
	v_mfma_f32_16x16x32_bf16 v[72:75], v[174:177], v[228:231], v[72:75]
	s_setprio 0
	s_setprio 1
	v_mfma_f32_16x16x32_bf16 v[116:119], v[178:181], v[200:203], 0
	v_mfma_f32_16x16x32_bf16 v[112:115], v[186:189], v[200:203], 0
	v_mfma_f32_16x16x32_bf16 v[100:103], v[178:181], v[208:211], 0
	v_mfma_f32_16x16x32_bf16 v[96:99], v[186:189], v[208:211], 0
	v_mfma_f32_16x16x32_bf16 v[84:87], v[178:181], v[216:219], 0
	v_mfma_f32_16x16x32_bf16 v[80:83], v[186:189], v[216:219], 0
	v_mfma_f32_16x16x32_bf16 v[68:71], v[178:181], v[224:227], 0
	v_mfma_f32_16x16x32_bf16 v[64:67], v[186:189], v[224:227], 0
	v_mfma_f32_16x16x32_bf16 v[116:119], v[182:185], v[204:207], v[116:119]
	v_mfma_f32_16x16x32_bf16 v[112:115], v[190:193], v[204:207], v[112:115]
	v_mfma_f32_16x16x32_bf16 v[100:103], v[182:185], v[212:215], v[100:103]
	v_mfma_f32_16x16x32_bf16 v[96:99], v[190:193], v[212:215], v[96:99]
	v_mfma_f32_16x16x32_bf16 v[84:87], v[182:185], v[220:223], v[84:87]
	v_mfma_f32_16x16x32_bf16 v[80:83], v[190:193], v[220:223], v[80:83]
	v_mfma_f32_16x16x32_bf16 v[68:71], v[182:185], v[228:231], v[68:71]
	v_mfma_f32_16x16x32_bf16 v[64:67], v[190:193], v[228:231], v[64:67]
	s_setprio 0
	s_barrier
	s_add_i32 s10, s12, s39
	v_lshl_add_u64 v[194:195], s[54:55], 0, v[132:133]
	s_mov_b32 m0, s10
	ds_read_b128 v[200:203], v161 offset:16384
	ds_read_b128 v[204:207], v161 offset:17408
	ds_read_b128 v[208:211], v161 offset:18432
	ds_read_b128 v[212:215], v161 offset:19456
	ds_read_b128 v[216:219], v161 offset:20480
	ds_read_b128 v[220:223], v161 offset:21504
	ds_read_b128 v[224:227], v161 offset:22528
	ds_read_b128 v[228:231], v161 offset:23552
	global_load_lds_dwordx4 v[194:195], off
	s_add_i32 m0, s10, 0x2000
	s_add_u32 s70, s54, 0x40000
	v_lshl_add_u64 v[240:241], s[54:55], 0, v[128:129]
	s_addc_u32 s71, s55, 0
	s_add_i32 s8, s8, s39
	global_load_lds_dwordx4 v[240:241], off
	v_lshl_add_u64 v[242:243], s[70:71], 0, v[132:133]
	s_mov_b32 m0, s8
	v_lshl_add_u64 v[244:245], s[56:57], 0, v[130:131]
	global_load_lds_dwordx4 v[242:243], off
	v_lshl_add_u64 v[242:243], s[70:71], 0, v[128:129]
	s_add_i32 m0, s8, 0x2000
	s_nop 0
	global_load_lds_dwordx4 v[242:243], off
	v_lshl_add_u64 v[242:243], s[56:57], 0, v[134:135]
	s_mov_b32 m0, s58
	s_nop 0
	global_load_lds_dwordx4 v[242:243], off
	s_mov_b32 m0, s59
	s_nop 0
	global_load_lds_dwordx4 v[244:245], off
	s_waitcnt vmcnt(26)
	s_waitcnt lgkmcnt(0)
	s_barrier
	s_setprio 1
	s_waitcnt lgkmcnt(0)
	v_mfma_f32_16x16x32_bf16 v[60:63], v[162:165], v[200:203], 0
	v_mfma_f32_16x16x32_bf16 v[56:59], v[170:173], v[200:203], 0
	v_mfma_f32_16x16x32_bf16 v[44:47], v[162:165], v[208:211], 0
	v_mfma_f32_16x16x32_bf16 v[40:43], v[170:173], v[208:211], 0
	v_mfma_f32_16x16x32_bf16 v[28:31], v[162:165], v[216:219], 0
	v_mfma_f32_16x16x32_bf16 v[24:27], v[170:173], v[216:219], 0
	v_mfma_f32_16x16x32_bf16 v[12:15], v[162:165], v[224:227], 0
	v_mfma_f32_16x16x32_bf16 v[8:11], v[170:173], v[224:227], 0
	v_mfma_f32_16x16x32_bf16 v[60:63], v[166:169], v[204:207], v[60:63]
	v_mfma_f32_16x16x32_bf16 v[56:59], v[174:177], v[204:207], v[56:59]
	v_mfma_f32_16x16x32_bf16 v[44:47], v[166:169], v[212:215], v[44:47]
	v_mfma_f32_16x16x32_bf16 v[40:43], v[174:177], v[212:215], v[40:43]
	v_mfma_f32_16x16x32_bf16 v[28:31], v[166:169], v[220:223], v[28:31]
	v_mfma_f32_16x16x32_bf16 v[24:27], v[174:177], v[220:223], v[24:27]
	v_mfma_f32_16x16x32_bf16 v[12:15], v[166:169], v[228:231], v[12:15]
	v_mfma_f32_16x16x32_bf16 v[8:11], v[174:177], v[228:231], v[8:11]
	s_setprio 0
	s_setprio 1
	v_mfma_f32_16x16x32_bf16 v[52:55], v[178:181], v[200:203], 0
	v_mfma_f32_16x16x32_bf16 v[48:51], v[186:189], v[200:203], 0
	v_mfma_f32_16x16x32_bf16 v[36:39], v[178:181], v[208:211], 0
	v_mfma_f32_16x16x32_bf16 v[32:35], v[186:189], v[208:211], 0
	v_mfma_f32_16x16x32_bf16 v[20:23], v[178:181], v[216:219], 0
	v_mfma_f32_16x16x32_bf16 v[16:19], v[186:189], v[216:219], 0
	v_mfma_f32_16x16x32_bf16 v[4:7], v[178:181], v[224:227], 0
	v_mfma_f32_16x16x32_bf16 v[0:3], v[186:189], v[224:227], 0
	v_mfma_f32_16x16x32_bf16 v[52:55], v[182:185], v[204:207], v[52:55]
	v_mfma_f32_16x16x32_bf16 v[48:51], v[190:193], v[204:207], v[48:51]
	v_mfma_f32_16x16x32_bf16 v[36:39], v[182:185], v[212:215], v[36:39]
	v_mfma_f32_16x16x32_bf16 v[32:35], v[190:193], v[212:215], v[32:35]
	v_mfma_f32_16x16x32_bf16 v[20:23], v[182:185], v[220:223], v[20:23]
	v_mfma_f32_16x16x32_bf16 v[16:19], v[190:193], v[220:223], v[16:19]
	v_mfma_f32_16x16x32_bf16 v[4:7], v[182:185], v[228:231], v[4:7]
	v_mfma_f32_16x16x32_bf16 v[0:3], v[190:193], v[228:231], v[0:3]
	s_setprio 0
	s_barrier
	s_branch .Lmid_g1e
